# P0(a) w_in transposes: item permutation so a workgroup's 8 waves read 8 adjacent column strips (1KB contiguous per row)
# baseline (speedup 1.0000x reference)
.LBB0_25:
	s_andn2_saveexec_b64 s[10:11], s[10:11]
	s_cbranch_execz .LBB0_8
	v_lshrrev_b32_e32 v243, 3, v1
	v_and_b32_e32 v244, 7, v1
	v_lshrrev_b32_e32 v245, 4, v243
	v_lshl_or_b32 v245, v245, 3, v244
	v_and_b32_e32 v243, 15, v243
	v_lshl_or_b32 v245, v245, 4, v243
	v_lshlrev_b32_e32 v243, 1, v245
	v_lshlrev_b32_e32 v244, 6, v245
	v_and_b32_e32 v73, 0xffffffe0, v243
	v_cmp_lt_i32_e32 vcc, s27, v73
	v_mov_b32_e32 v24, v73
	s_and_saveexec_b64 s[12:13], vcc
	s_cbranch_execz .LBB0_36
	v_cmp_lt_u32_e32 vcc, s28, v243
	s_and_saveexec_b64 s[14:15], vcc
	s_xor_b64 s[14:15], exec, s[14:15]
	s_cbranch_execz .LBB0_33
	v_cmp_lt_u32_e32 vcc, s29, v243
	s_and_saveexec_b64 s[16:17], vcc
	s_xor_b64 s[16:17], exec, s[16:17]
	v_or_b32_e32 v24, 16, v73
	s_andn2_saveexec_b64 s[16:17], s[16:17]
	v_add_u32_e32 v24, 0xfffffc00, v73
	s_or_b64 exec, exec, s[16:17]

.LBB0_36:
	s_or_b64 exec, exec, s[12:13]
	v_and_b32_e32 v74, 0x3c0, v244
	v_or_b32_e32 v75, v74, v56
	v_ashrrev_i32_e32 v25, 31, v24
	v_mul_u32_u24_e32 v2, 0x1210, v75
	v_lshl_add_u64 v[48:49], v[24:25], 2, v[22:23]
	v_lshlrev_b32_e32 v2, 2, v2
	v_lshl_add_u64 v[24:25], v[48:49], 0, v[2:3]
	v_add_co_u32_e32 v26, vcc, 0x9000, v24
	v_add_u32_e32 v30, 0x1b180, v2
	s_nop 0
	v_addc_co_u32_e32 v27, vcc, 0, v25, vcc
	v_add_co_u32_e32 v28, vcc, s26, v24
	v_mov_b32_e32 v31, v3
	v_add_u32_e32 v32, 0x24200, v2
	v_mov_b32_e32 v33, v3
	v_add_u32_e32 v34, 0x2d280, v2
	v_mov_b32_e32 v35, v3
	v_add_u32_e32 v36, 0x36300, v2
	v_mov_b32_e32 v37, v3
	v_add_u32_e32 v38, 0x3f380, v2
	v_mov_b32_e32 v39, v3
	v_addc_co_u32_e32 v29, vcc, 0, v25, vcc
	v_lshl_add_u64 v[30:31], v[48:49], 0, v[30:31]
	v_lshl_add_u64 v[32:33], v[48:49], 0, v[32:33]
	v_lshl_add_u64 v[34:35], v[48:49], 0, v[34:35]
	v_lshl_add_u64 v[36:37], v[48:49], 0, v[36:37]
	v_lshl_add_u64 v[38:39], v[48:49], 0, v[38:39]
	global_load_dword v24, v[24:25], off
	s_nop 0
	global_load_dword v25, v[26:27], off offset:128
	s_nop 0
	global_load_dword v26, v[28:29], off offset:256
	global_load_dword v27, v[30:31], off
	s_nop 0
	global_load_dword v28, v[32:33], off
	global_load_dword v29, v[34:35], off
	global_load_dword v30, v[36:37], off
	global_load_dword v31, v[38:39], off
	v_add_u32_e32 v32, 0x48400, v2
	v_mov_b32_e32 v33, v3
	v_add_u32_e32 v34, 0x51480, v2
	v_mov_b32_e32 v35, v3
	v_add_u32_e32 v36, 0x5a500, v2
	v_mov_b32_e32 v37, v3
	v_add_u32_e32 v38, 0x63580, v2
	v_mov_b32_e32 v39, v3
	v_add_u32_e32 v40, 0x6c600, v2
	v_mov_b32_e32 v41, v3
	v_add_u32_e32 v42, 0x75680, v2
	v_mov_b32_e32 v43, v3
	v_add_u32_e32 v44, 0x7e700, v2
	v_mov_b32_e32 v45, v3
	v_add_u32_e32 v46, 0x87780, v2
	v_mov_b32_e32 v47, v3
	v_lshl_add_u64 v[32:33], v[48:49], 0, v[32:33]
	v_lshl_add_u64 v[34:35], v[48:49], 0, v[34:35]
	v_lshl_add_u64 v[36:37], v[48:49], 0, v[36:37]
	v_lshl_add_u64 v[38:39], v[48:49], 0, v[38:39]
	v_lshl_add_u64 v[40:41], v[48:49], 0, v[40:41]
	v_lshl_add_u64 v[42:43], v[48:49], 0, v[42:43]
	v_lshl_add_u64 v[44:45], v[48:49], 0, v[44:45]
	v_lshl_add_u64 v[46:47], v[48:49], 0, v[46:47]
	global_load_dword v32, v[32:33], off
	s_nop 0
	global_load_dword v33, v[34:35], off
	s_nop 0
	global_load_dword v34, v[36:37], off
	global_load_dword v35, v[38:39], off
	s_nop 0
	global_load_dword v36, v[40:41], off
	global_load_dword v37, v[42:43], off
	global_load_dword v38, v[44:45], off
	global_load_dword v39, v[46:47], off
	v_add_u32_e32 v40, 0x90800, v2
	v_mov_b32_e32 v41, v3
	v_add_u32_e32 v42, 0x99880, v2
	v_mov_b32_e32 v43, v3
	v_add_u32_e32 v44, 0xa2900, v2
	v_mov_b32_e32 v45, v3
	v_add_u32_e32 v46, 0xab980, v2
	v_mov_b32_e32 v47, v3
	v_add_u32_e32 v50, 0xb4a00, v2
	v_mov_b32_e32 v51, v3
	v_add_u32_e32 v52, 0xbda80, v2
	v_mov_b32_e32 v53, v3
	v_add_u32_e32 v54, 0xc6b00, v2
	v_mov_b32_e32 v55, v3
	v_lshl_add_u64 v[40:41], v[48:49], 0, v[40:41]
	v_lshl_add_u64 v[42:43], v[48:49], 0, v[42:43]
	v_lshl_add_u64 v[44:45], v[48:49], 0, v[44:45]
	v_lshl_add_u64 v[46:47], v[48:49], 0, v[46:47]
	v_lshl_add_u64 v[50:51], v[48:49], 0, v[50:51]
	v_lshl_add_u64 v[52:53], v[48:49], 0, v[52:53]
	v_lshl_add_u64 v[54:55], v[48:49], 0, v[54:55]
	v_add_u32_e32 v76, 0xcfb80, v2
	v_mov_b32_e32 v77, v3
	v_lshl_add_u64 v[76:77], v[48:49], 0, v[76:77]
	global_load_dword v40, v[40:41], off
	s_nop 0
	global_load_dword v41, v[42:43], off
	s_nop 0
	global_load_dword v42, v[44:45], off
	global_load_dword v43, v[46:47], off
	s_nop 0
	global_load_dword v44, v[50:51], off
	global_load_dword v45, v[52:53], off
	global_load_dword v46, v[54:55], off
	global_load_dword v47, v[76:77], off
	v_add_u32_e32 v50, 0xd8c00, v2
	v_mov_b32_e32 v51, v3
	v_add_u32_e32 v52, 0xe1c80, v2
	v_mov_b32_e32 v53, v3
	v_add_u32_e32 v54, 0xead00, v2
	v_mov_b32_e32 v55, v3
	v_lshl_add_u64 v[50:51], v[48:49], 0, v[50:51]
	v_lshl_add_u64 v[52:53], v[48:49], 0, v[52:53]
	v_lshl_add_u64 v[54:55], v[48:49], 0, v[54:55]
	v_add_u32_e32 v76, 0xf3d80, v2
	v_mov_b32_e32 v77, v3
	v_add_u32_e32 v78, 0xfce00, v2
	v_mov_b32_e32 v79, v3
	v_add_u32_e32 v80, 0x105e80, v2
	v_mov_b32_e32 v81, v3
	v_add_u32_e32 v84, 0x10ef00, v2
	v_mov_b32_e32 v85, v3
	v_add_u32_e32 v2, 0x117f80, v2
	v_lshl_add_u64 v[76:77], v[48:49], 0, v[76:77]
	v_lshl_add_u64 v[78:79], v[48:49], 0, v[78:79]
	v_lshl_add_u64 v[80:81], v[48:49], 0, v[80:81]
	v_lshl_add_u64 v[84:85], v[48:49], 0, v[84:85]
	v_lshl_add_u64 v[86:87], v[48:49], 0, v[2:3]
	global_load_dword v48, v[50:51], off
	global_load_dword v49, v[52:53], off
	s_nop 0
	global_load_dword v50, v[54:55], off
	global_load_dword v51, v[76:77], off
	s_nop 0
	global_load_dword v54, v[78:79], off
	global_load_dword v55, v[80:81], off
	global_load_dword v52, v[84:85], off
	global_load_dword v53, v[86:87], off
	s_andn2_b64 vcc, exec, s[8:9]
	s_cbranch_vccnz .LBB0_7
	s_load_dwordx16 s[36:51], s[0:1], 0x40
	v_lshlrev_b32_e32 v2, 2, v75
	s_waitcnt lgkmcnt(0)
	global_load_dword v76, v2, s[38:39]
	global_load_dword v77, v2, s[38:39] offset:8
	global_load_dword v78, v2, s[38:39] offset:16
	global_load_dword v79, v2, s[38:39] offset:24
	global_load_dword v80, v2, s[38:39] offset:32
	global_load_dword v81, v2, s[38:39] offset:40
	global_load_dword v84, v2, s[38:39] offset:48
	global_load_dword v85, v2, s[38:39] offset:56
	global_load_dword v86, v2, s[38:39] offset:64
	global_load_dword v87, v2, s[38:39] offset:72
	global_load_dword v88, v2, s[38:39] offset:80
	global_load_dword v89, v2, s[38:39] offset:88
	global_load_dword v90, v2, s[38:39] offset:96
	global_load_dword v91, v2, s[38:39] offset:104
	global_load_dword v92, v2, s[38:39] offset:112
	global_load_dword v93, v2, s[38:39] offset:120
	global_load_dword v94, v2, s[38:39] offset:128
	global_load_dword v95, v2, s[38:39] offset:136
	global_load_dword v96, v2, s[38:39] offset:144
	global_load_dword v97, v2, s[38:39] offset:152
	global_load_dword v98, v2, s[38:39] offset:160
	global_load_dword v99, v2, s[38:39] offset:168
	global_load_dword v100, v2, s[38:39] offset:176
	global_load_dword v101, v2, s[38:39] offset:184
	global_load_dword v102, v2, s[38:39] offset:192
	global_load_dword v103, v2, s[38:39] offset:200
	global_load_dword v104, v2, s[38:39] offset:208
	global_load_dword v105, v2, s[38:39] offset:216
	global_load_dword v106, v2, s[38:39] offset:224
	global_load_dword v107, v2, s[38:39] offset:232
	global_load_dword v108, v2, s[38:39] offset:240
	global_load_dword v109, v2, s[38:39] offset:248
	s_waitcnt vmcnt(30)
	v_pk_mul_f32 v[24:25], v[24:25], v[76:77]
	s_waitcnt vmcnt(28)
	v_pk_mul_f32 v[26:27], v[26:27], v[78:79]
	s_waitcnt vmcnt(26)
	v_pk_mul_f32 v[28:29], v[28:29], v[80:81]
	s_waitcnt vmcnt(24)
	v_pk_mul_f32 v[30:31], v[30:31], v[84:85]
	s_waitcnt vmcnt(22)
	v_pk_mul_f32 v[32:33], v[32:33], v[86:87]
	s_waitcnt vmcnt(20)
	v_pk_mul_f32 v[34:35], v[34:35], v[88:89]
	s_waitcnt vmcnt(18)
	v_pk_mul_f32 v[36:37], v[36:37], v[90:91]
	s_waitcnt vmcnt(16)
	v_pk_mul_f32 v[38:39], v[38:39], v[92:93]
	s_waitcnt vmcnt(14)
	v_pk_mul_f32 v[40:41], v[40:41], v[94:95]
	s_waitcnt vmcnt(12)
	v_pk_mul_f32 v[42:43], v[42:43], v[96:97]
	s_waitcnt vmcnt(10)
	v_pk_mul_f32 v[44:45], v[44:45], v[98:99]
	s_waitcnt vmcnt(8)
	v_pk_mul_f32 v[46:47], v[46:47], v[100:101]
	s_waitcnt vmcnt(6)
	v_pk_mul_f32 v[48:49], v[48:49], v[102:103]
	s_waitcnt vmcnt(4)
	v_pk_mul_f32 v[50:51], v[50:51], v[104:105]
	s_waitcnt vmcnt(2)
	v_pk_mul_f32 v[54:55], v[54:55], v[106:107]
	s_waitcnt vmcnt(0)
	v_pk_mul_f32 v[52:53], v[52:53], v[108:109]
	s_branch .LBB0_7
